# HG p4 (P4): next item's S_prev block prefetched into spare VGPRs while the current item computes; on top of acquire-at-arrival
# baseline (speedup 1.0000x reference)
.LBB0_1085:
	s_or_b64 exec, exec, s[0:1]
	s_cmpk_gt_i32 s2, 0x8bf
	s_barrier
	s_cbranch_scc1 .LBB0_1096
	s_add_u32 s13, s20, 0x17348000
	s_addc_u32 s15, s21, 0
	s_add_u32 s29, s20, 0x15248000
	s_addc_u32 s39, s21, 0
	s_add_u32 s46, s50, 0x4200000
	s_addc_u32 s47, s51, 0
	s_add_u32 s56, s50, 0x2100000
	s_addc_u32 s57, s51, 0
	s_waitcnt vmcnt(27)
	v_mbcnt_hi_u32_b32 v40, -1, v183
	s_add_u32 s58, s20, 0x19448000
	v_and_b32_e32 v0, 64, v40
	s_addc_u32 s59, s21, 0
	s_lshl_b32 s60, s2, 7
	s_lshl_b32 s61, s22, 7
	s_movk_i32 s62, 0x6000
	s_mov_b32 s7, 0
	v_mov_b32_e32 v33, 0
	s_mov_b64 s[8:9], 0x1000
	s_mov_b64 s[10:11], 0x1800
	s_movk_i32 s63, 0x1000
	s_mov_b32 s12, 0x3c800000
	s_mov_b32 s14, 0x358637bd
	s_mov_b32 s64, 0x800000
	s_movk_i32 s65, 0x2000
	s_movk_i32 s66, 0x4000
	s_mov_b64 s[16:17], 0x1c00
	s_movk_i32 s67, 0x3000
	s_movk_i32 s68, 0x5000
	s_movk_i32 s69, 0x7000
	s_mov_b64 s[34:35], 0x80
	s_mov_b64 s[36:37], 0xc0
	s_brev_b32 s38, 60
	v_xor_b32_e32 v41, 1, v40
	v_add_u32_e32 v42, 64, v0
	v_xor_b32_e32 v43, 2, v40
	s_waitcnt vmcnt(26)
	v_xor_b32_e32 v44, 4, v40
	v_xor_b32_e32 v45, 8, v40
	s_mov_b32 s70, s2
	v_bfe_u32 v232, v181, 4, 2
	v_lshlrev_b32_e32 v232, 4, v232
	global_load_dwordx4 v[184:187], v232, s[44:45]
	global_load_dwordx4 v[188:191], v232, s[44:45] offset:64
	global_load_dwordx4 v[192:195], v232, s[44:45] offset:128
	global_load_dwordx4 v[196:199], v232, s[44:45] offset:192
	global_load_dwordx4 v[200:203], v232, s[44:45] offset:256
	global_load_dwordx4 v[204:207], v232, s[44:45] offset:320
	global_load_dwordx4 v[208:211], v232, s[44:45] offset:384
	global_load_dwordx4 v[212:215], v232, s[44:45] offset:448
	s_mov_b32 s71, 0
	s_branch .LBB0_1089

.LBB0_1094:
	s_ashr_i32 s4, s70, 2
	v_and_b32_e32 v0, 63, v181
	s_cmpk_gt_i32 s4, 0x1ff
	s_cselect_b64 s[0:1], -1, 0
	v_ashrrev_i32_e32 v1, 6, v181
	s_cmpk_lt_i32 s4, 0x200
	s_cselect_b64 s[24:25], -1, 0
	v_cmp_gt_i32_e32 vcc, 1, v1
	s_nop 1
	s_or_b64 s[42:43], s[24:25], vcc
	s_lshl_b32 s5, s4, 4
	s_addk_i32 s5, 0x6000
	s_lshl_b32 s6, s4, 6
	s_and_b64 s[0:1], s[0:1], exec
	s_cselect_b32 s0, s5, s6
	s_and_b32 s5, s70, 0xfffffe00
	s_bfe_u32 s6, s70, 0x70002
	s_and_b32 s1, s60, 0x180
	s_or_b32 s5, s6, s5
	s_or_b32 s5, s5, s1
	s_lshr_b32 s98, s4, 2
	s_lshl_b32 s98, s98, 21
	s_and_b32 s99, s4, 3
	s_lshl_b32 s99, s99, 14
	s_or_b32 s98, s98, s99
	s_lshl_b32 s99, s1, 11
	s_add_u32 s98, s98, s99
	s_add_u32 s98, s98, 0x100000
	s_cmpk_lt_i32 s4, 0x200
	s_cselect_b64 s[100:101], -1, 0
	s_cselect_b32 s99, 0x10000, 64
	s_cmpk_lt_i32 s4, 0x200
	s_cselect_b32 s4, s5, s70
	s_ashr_i32 s5, s4, 31
	s_lshl_b64 s[24:25], s[4:5], 14
	s_add_u32 s30, s46, s24
	s_addc_u32 s31, s47, s25
	s_add_u32 s24, s56, s24
	s_addc_u32 s25, s57, s25
	s_lshl_b64 s[4:5], s[4:5], 15
	s_add_u32 s4, s58, s4
	s_addc_u32 s5, s59, s5
	v_and_b32_e32 v2, 15, v181
	v_bfe_u32 v3, v181, 4, 2
	v_lshlrev_b32_e32 v4, 3, v0
	v_lshl_add_u32 v4, v1, 12, v4
	v_lshl_add_u32 v5, v1, 4, v2
	v_lshlrev_b32_e32 v5, 8, v5
	v_lshl_add_u32 v5, v3, 4, v5
	v_lshlrev_b32_e32 v6, 4, v181
	v_add_u32_e32 v7, 0x1000, v6
	v_add_u32_e32 v8, 0x2000, v6
	v_add_u32_e32 v9, 0x3000, v6
	v_add_u32_e32 v10, 0x4000, v6
	v_add_u32_e32 v11, 0x5000, v6
	v_add_u32_e32 v12, 0x6000, v6
	v_add_u32_e32 v13, 0x7000, v6
	v_lshrrev_b32_e32 v16, 4, v181
	v_mul_u32_u24_e32 v16, 272, v16
	v_lshl_add_u32 v16, v2, 4, v16
	v_mul_u32_u24_e32 v233, 272, v2
	v_lshl_add_u32 v233, v3, 4, v233
	v_lshl_add_u32 v14, v1, 4, s0
	v_add_u32_e32 v14, v14, v2
	v_lshlrev_b32_e32 v14, 13, v14
	v_lshlrev_b32_e32 v15, 3, v3
	v_add_u32_e32 v14, v14, v15
	s_lshl_b32 s6, s1, 1
	s_add_i32 s6, s6, 0x400
	v_add_u32_e32 v232, s6, v14
	v_add_u32_e32 v14, 0x1800, v232
	v_lshrrev_b32_e32 v234, 1, v1
	v_lshlrev_b32_e32 v234, 13, v234
	v_and_b32_e32 v235, 1, v1
	v_lshl_or_b32 v234, v235, 10, v234
	v_lshl_or_b32 v234, v2, 6, v234
	v_lshrrev_b32_e32 v235, 1, v3
	v_bfe_u32 v236, v2, 1, 2
	v_xor_b32_e32 v235, v235, v236
	v_lshl_or_b32 v234, v235, 4, v234
	v_and_b32_e32 v235, 1, v3
	v_lshl_or_b32 v234, v235, 3, v234
	v_add_u32_e32 v234, s98, v234
	v_cndmask_b32_e64 v232, v232, v234, s[100:101]
	v_xor_b32_e32 v234, 32, v232
	global_load_dwordx2 v[62:63], v4, s[30:31]
	global_load_dwordx2 v[64:65], v4, s[30:31] offset:512
	global_load_dwordx2 v[66:67], v4, s[30:31] offset:1024
	global_load_dwordx2 v[68:69], v4, s[30:31] offset:1536
	global_load_dwordx2 v[70:71], v4, s[30:31] offset:2048
	global_load_dwordx2 v[72:73], v4, s[30:31] offset:2560
	global_load_dwordx2 v[74:75], v4, s[30:31] offset:3072
	global_load_dwordx2 v[76:77], v4, s[30:31] offset:3584
	global_load_dwordx4 v[46:49], v5, s[24:25]
	global_load_dwordx4 v[50:53], v5, s[24:25] offset:64
	global_load_dwordx4 v[54:57], v5, s[24:25] offset:128
	global_load_dwordx4 v[58:61], v5, s[24:25] offset:192
	global_load_dwordx2 v[216:217], v14, s[20:21]
	global_load_dwordx2 v[218:219], v14, s[20:21] offset:32
	global_load_dwordx2 v[220:221], v14, s[20:21] offset:64
	global_load_dwordx2 v[222:223], v14, s[20:21] offset:96
	global_load_dwordx2 v[224:225], v14, s[20:21] offset:128
	global_load_dwordx2 v[226:227], v14, s[20:21] offset:160
	global_load_dwordx2 v[228:229], v14, s[20:21] offset:192
	global_load_dwordx2 v[230:231], v14, s[20:21] offset:224
	s_cmp_lg_u32 s71, 0
	s_cbranch_scc1 .Lp4_skipS
	global_load_dwordx4 v[142:145], v6, s[4:5]
	global_load_dwordx4 v[146:149], v7, s[4:5]
	global_load_dwordx4 v[150:153], v8, s[4:5]
	global_load_dwordx4 v[154:157], v9, s[4:5]
	global_load_dwordx4 v[158:161], v10, s[4:5]
	global_load_dwordx4 v[162:165], v11, s[4:5]
	global_load_dwordx4 v[166:169], v12, s[4:5]
	global_load_dwordx4 v[170:173], v13, s[4:5]
.Lp4_skipS:
	s_barrier
	s_waitcnt vmcnt(0)
	ds_write_b128 v16, v[142:145]
	ds_write_b128 v16, v[146:149] offset:4352
	ds_write_b128 v16, v[150:153] offset:8704
	ds_write_b128 v16, v[154:157] offset:13056
	ds_write_b128 v16, v[158:161] offset:17408
	ds_write_b128 v16, v[162:165] offset:21760
	ds_write_b128 v16, v[166:169] offset:26112
	ds_write_b128 v16, v[170:173] offset:30464
	s_waitcnt lgkmcnt(0)
	s_add_i32 s72, s70, s22
	s_mov_b32 s71, 0
	s_cmpk_gt_i32 s72, 0x83f
	s_cbranch_scc1 .Lp4_nopf
	s_add_i32 s73, s60, s61
	s_ashr_i32 s74, s72, 2
	s_and_b32 s75, s72, 0xfffffe00
	s_bfe_u32 s76, s72, 0x70002
	s_and_b32 s77, s73, 0x180
	s_or_b32 s75, s76, s75
	s_or_b32 s75, s75, s77
	s_cmpk_lt_i32 s74, 0x200
	s_cselect_b32 s74, s75, s72
	s_ashr_i32 s75, s74, 31
	s_lshl_b64 s[74:75], s[74:75], 15
	s_add_u32 s74, s58, s74
	s_addc_u32 s75, s59, s75
	global_load_dwordx4 v[142:145], v6, s[74:75]
	global_load_dwordx4 v[146:149], v7, s[74:75]
	global_load_dwordx4 v[150:153], v8, s[74:75]
	global_load_dwordx4 v[154:157], v9, s[74:75]
	global_load_dwordx4 v[158:161], v10, s[74:75]
	global_load_dwordx4 v[162:165], v11, s[74:75]
	global_load_dwordx4 v[166:169], v12, s[74:75]
	global_load_dwordx4 v[170:173], v13, s[74:75]
	s_mov_b32 s71, 1
.Lp4_nopf:
	s_barrier
	s_mov_b64 vcc, s[42:43]
	s_and_saveexec_b64 s[42:43], vcc
	s_cbranch_execz .LBB0_1087
	v_lshlrev_b32_e32 v28, 16, v62
	v_and_b32_e32 v29, 0xffff0000, v62
	v_lshlrev_b32_e32 v30, 16, v63
	v_and_b32_e32 v31, 0xffff0000, v63
	v_lshlrev_b32_e32 v24, 16, v64
	v_and_b32_e32 v25, 0xffff0000, v64
	v_lshlrev_b32_e32 v26, 16, v65
	v_and_b32_e32 v27, 0xffff0000, v65
	v_lshlrev_b32_e32 v20, 16, v66
	v_and_b32_e32 v21, 0xffff0000, v66
	v_lshlrev_b32_e32 v22, 16, v67
	v_and_b32_e32 v23, 0xffff0000, v67
	v_lshlrev_b32_e32 v16, 16, v68
	v_and_b32_e32 v17, 0xffff0000, v68
	v_lshlrev_b32_e32 v18, 16, v69
	v_and_b32_e32 v19, 0xffff0000, v69
	v_lshlrev_b32_e32 v12, 16, v70
	v_and_b32_e32 v13, 0xffff0000, v70
	v_lshlrev_b32_e32 v14, 16, v71
	v_and_b32_e32 v15, 0xffff0000, v71
	v_lshlrev_b32_e32 v8, 16, v72
	v_and_b32_e32 v9, 0xffff0000, v72
	v_lshlrev_b32_e32 v10, 16, v73
	v_and_b32_e32 v11, 0xffff0000, v73
	v_lshlrev_b32_e32 v4, 16, v74
	v_and_b32_e32 v5, 0xffff0000, v74
	v_lshlrev_b32_e32 v6, 16, v75
	v_and_b32_e32 v7, 0xffff0000, v75
	v_lshlrev_b32_e32 v0, 16, v76
	v_and_b32_e32 v1, 0xffff0000, v76
	v_lshlrev_b32_e32 v2, 16, v77
	v_and_b32_e32 v3, 0xffff0000, v77
	ds_read_b128 v[78:81], v233 offset:0
	ds_read_b128 v[82:85], v233 offset:4352
	ds_read_b128 v[86:89], v233 offset:8704
	ds_read_b128 v[90:93], v233 offset:13056
	ds_read_b128 v[94:97], v233 offset:17408
	ds_read_b128 v[98:101], v233 offset:21760
	ds_read_b128 v[102:105], v233 offset:26112
	ds_read_b128 v[106:109], v233 offset:30464
	s_waitcnt lgkmcnt(4)
	ds_read_b128 v[110:113], v233 offset:64
	ds_read_b128 v[114:117], v233 offset:4416
	ds_read_b128 v[118:121], v233 offset:8768
	ds_read_b128 v[122:125], v233 offset:13120
	ds_read_b128 v[126:129], v233 offset:17472
	ds_read_b128 v[130:133], v233 offset:21824
	ds_read_b128 v[134:137], v233 offset:26176
	ds_read_b128 v[138:141], v233 offset:30528
	s_waitcnt lgkmcnt(8)
	v_mfma_f32_16x16x32_bf16 v[28:31], v[78:81], v[46:49], v[28:31]
	v_mfma_f32_16x16x32_bf16 v[24:27], v[82:85], v[46:49], v[24:27]
	v_mfma_f32_16x16x32_bf16 v[20:23], v[86:89], v[46:49], v[20:23]
	v_mfma_f32_16x16x32_bf16 v[16:19], v[90:93], v[46:49], v[16:19]
	v_mfma_f32_16x16x32_bf16 v[12:15], v[94:97], v[46:49], v[12:15]
	v_mfma_f32_16x16x32_bf16 v[8:11], v[98:101], v[46:49], v[8:11]
	v_mfma_f32_16x16x32_bf16 v[4:7], v[102:105], v[46:49], v[4:7]
	v_mfma_f32_16x16x32_bf16 v[0:3], v[106:109], v[46:49], v[0:3]
	s_waitcnt lgkmcnt(4)
	ds_read_b128 v[78:81], v233 offset:128
	ds_read_b128 v[82:85], v233 offset:4480
	ds_read_b128 v[86:89], v233 offset:8832
	ds_read_b128 v[90:93], v233 offset:13184
	ds_read_b128 v[94:97], v233 offset:17536
	ds_read_b128 v[98:101], v233 offset:21888
	ds_read_b128 v[102:105], v233 offset:26240
	ds_read_b128 v[106:109], v233 offset:30592
	s_waitcnt lgkmcnt(8)
	v_mfma_f32_16x16x32_bf16 v[28:31], v[110:113], v[50:53], v[28:31]
	v_mfma_f32_16x16x32_bf16 v[24:27], v[114:117], v[50:53], v[24:27]
	v_mfma_f32_16x16x32_bf16 v[20:23], v[118:121], v[50:53], v[20:23]
	v_mfma_f32_16x16x32_bf16 v[16:19], v[122:125], v[50:53], v[16:19]
	v_mfma_f32_16x16x32_bf16 v[12:15], v[126:129], v[50:53], v[12:15]
	v_mfma_f32_16x16x32_bf16 v[8:11], v[130:133], v[50:53], v[8:11]
	v_mfma_f32_16x16x32_bf16 v[4:7], v[134:137], v[50:53], v[4:7]
	v_mfma_f32_16x16x32_bf16 v[0:3], v[138:141], v[50:53], v[0:3]
	s_waitcnt lgkmcnt(4)
	ds_read_b128 v[110:113], v233 offset:192
	ds_read_b128 v[114:117], v233 offset:4544
	ds_read_b128 v[118:121], v233 offset:8896
	ds_read_b128 v[122:125], v233 offset:13248
	ds_read_b128 v[126:129], v233 offset:17600
	ds_read_b128 v[130:133], v233 offset:21952
	ds_read_b128 v[134:137], v233 offset:26304
	ds_read_b128 v[138:141], v233 offset:30656
	s_waitcnt lgkmcnt(8)
	v_mfma_f32_16x16x32_bf16 v[28:31], v[78:81], v[54:57], v[28:31]
	v_mfma_f32_16x16x32_bf16 v[24:27], v[82:85], v[54:57], v[24:27]
	v_mfma_f32_16x16x32_bf16 v[20:23], v[86:89], v[54:57], v[20:23]
	v_mfma_f32_16x16x32_bf16 v[16:19], v[90:93], v[54:57], v[16:19]
	v_mfma_f32_16x16x32_bf16 v[12:15], v[94:97], v[54:57], v[12:15]
	v_mfma_f32_16x16x32_bf16 v[8:11], v[98:101], v[54:57], v[8:11]
	v_mfma_f32_16x16x32_bf16 v[4:7], v[102:105], v[54:57], v[4:7]
	v_mfma_f32_16x16x32_bf16 v[0:3], v[106:109], v[54:57], v[0:3]
	s_waitcnt lgkmcnt(0)
	v_mfma_f32_16x16x32_bf16 v[28:31], v[110:113], v[58:61], v[28:31]
	v_mfma_f32_16x16x32_bf16 v[24:27], v[114:117], v[58:61], v[24:27]
	v_mfma_f32_16x16x32_bf16 v[20:23], v[118:121], v[58:61], v[20:23]
	v_mfma_f32_16x16x32_bf16 v[16:19], v[122:125], v[58:61], v[16:19]
	v_mfma_f32_16x16x32_bf16 v[12:15], v[126:129], v[58:61], v[12:15]
	v_mfma_f32_16x16x32_bf16 v[8:11], v[130:133], v[58:61], v[8:11]
	v_mfma_f32_16x16x32_bf16 v[4:7], v[134:137], v[58:61], v[4:7]
	v_mfma_f32_16x16x32_bf16 v[0:3], v[138:141], v[58:61], v[0:3]
	v_xor_b32_e32 v241, 16, v40
	v_xor_b32_e32 v242, 32, v40
	v_lshlrev_b32_e32 v241, 2, v241
	v_lshlrev_b32_e32 v242, 2, v242
	s_nop 4
	v_mul_f32_e32 v46, v28, v28
	v_fmac_f32_e32 v46, v29, v29
	v_fmac_f32_e32 v46, v30, v30
	v_fmac_f32_e32 v46, v31, v31
	v_fmac_f32_e32 v46, v24, v24
	v_fmac_f32_e32 v46, v25, v25
	v_fmac_f32_e32 v46, v26, v26
	v_fmac_f32_e32 v46, v27, v27
	v_fmac_f32_e32 v46, v20, v20
	v_fmac_f32_e32 v46, v21, v21
	v_fmac_f32_e32 v46, v22, v22
	v_fmac_f32_e32 v46, v23, v23
	v_fmac_f32_e32 v46, v16, v16
	v_fmac_f32_e32 v46, v17, v17
	v_fmac_f32_e32 v46, v18, v18
	v_fmac_f32_e32 v46, v19, v19
	v_fmac_f32_e32 v46, v12, v12
	v_fmac_f32_e32 v46, v13, v13
	v_fmac_f32_e32 v46, v14, v14
	v_fmac_f32_e32 v46, v15, v15
	v_fmac_f32_e32 v46, v8, v8
	v_fmac_f32_e32 v46, v9, v9
	v_fmac_f32_e32 v46, v10, v10
	v_fmac_f32_e32 v46, v11, v11
	v_fmac_f32_e32 v46, v4, v4
	v_fmac_f32_e32 v46, v5, v5
	v_fmac_f32_e32 v46, v6, v6
	v_fmac_f32_e32 v46, v7, v7
	v_fmac_f32_e32 v46, v0, v0
	v_fmac_f32_e32 v46, v1, v1
	v_fmac_f32_e32 v46, v2, v2
	v_fmac_f32_e32 v46, v3, v3
	ds_bpermute_b32 v47, v241, v46
	s_waitcnt lgkmcnt(0)
	v_add_f32_e32 v46, v46, v47
	ds_bpermute_b32 v47, v242, v46
	s_waitcnt lgkmcnt(0)
	v_add_f32_e32 v46, v46, v47
	v_mov_b32_e32 v50, 0x358637bd
	v_fmamk_f32 v46, v46, 0x3c000000, v50
	v_rsq_f32_e32 v46, v46
	v_lshlrev_b32_e32 v48, 16, v216
	v_and_b32_e32 v49, 0xffff0000, v216
	v_lshlrev_b32_e32 v50, 16, v217
	v_and_b32_e32 v51, 0xffff0000, v217
	v_mul_f32_e32 v52, 0xbfb8aa3b, v48
	v_mul_f32_e32 v53, 0xbfb8aa3b, v49
	v_mul_f32_e32 v54, 0xbfb8aa3b, v50
	v_mul_f32_e32 v55, 0xbfb8aa3b, v51
	v_exp_f32_e32 v52, v52
	v_exp_f32_e32 v53, v53
	v_exp_f32_e32 v54, v54
	v_exp_f32_e32 v55, v55
	v_mul_f32_e32 v56, v28, v46
	v_mul_f32_e32 v57, v29, v46
	v_mul_f32_e32 v58, v30, v46
	v_mul_f32_e32 v59, v31, v46
	v_add_f32_e32 v52, 1.0, v52
	v_add_f32_e32 v53, 1.0, v53
	v_add_f32_e32 v54, 1.0, v54
	v_add_f32_e32 v55, 1.0, v55
	v_rcp_f32_e32 v52, v52
	v_rcp_f32_e32 v53, v53
	v_rcp_f32_e32 v54, v54
	v_rcp_f32_e32 v55, v55
	v_mul_f32_e32 v56, v184, v56
	v_mul_f32_e32 v57, v185, v57
	v_mul_f32_e32 v58, v186, v58
	v_mul_f32_e32 v59, v187, v59
	v_mul_f32_e32 v52, v52, v48
	v_mul_f32_e32 v53, v53, v49
	v_mul_f32_e32 v54, v54, v50
	v_mul_f32_e32 v55, v55, v51
	v_mul_f32_e32 v56, v52, v56
	v_mul_f32_e32 v57, v53, v57
	v_mul_f32_e32 v58, v54, v58
	v_mul_f32_e32 v59, v55, v59
	v_cvt_pk_bf16_f32 v60, v56, v57
	v_cvt_pk_bf16_f32 v61, v58, v59
	s_mov_b64 s[24:25], s[20:21]
	global_store_dwordx2 v232, v[60:61], s[24:25]
	v_lshlrev_b32_e32 v48, 16, v218
	v_and_b32_e32 v49, 0xffff0000, v218
	v_lshlrev_b32_e32 v50, 16, v219
	v_and_b32_e32 v51, 0xffff0000, v219
	v_mul_f32_e32 v52, 0xbfb8aa3b, v48
	v_mul_f32_e32 v53, 0xbfb8aa3b, v49
	v_mul_f32_e32 v54, 0xbfb8aa3b, v50
	v_mul_f32_e32 v55, 0xbfb8aa3b, v51
	v_exp_f32_e32 v52, v52
	v_exp_f32_e32 v53, v53
	v_exp_f32_e32 v54, v54
	v_exp_f32_e32 v55, v55
	v_mul_f32_e32 v56, v24, v46
	v_mul_f32_e32 v57, v25, v46
	v_mul_f32_e32 v58, v26, v46
	v_mul_f32_e32 v59, v27, v46
	v_add_f32_e32 v52, 1.0, v52
	v_add_f32_e32 v53, 1.0, v53
	v_add_f32_e32 v54, 1.0, v54
	v_add_f32_e32 v55, 1.0, v55
	v_rcp_f32_e32 v52, v52
	v_rcp_f32_e32 v53, v53
	v_rcp_f32_e32 v54, v54
	v_rcp_f32_e32 v55, v55
	v_mul_f32_e32 v56, v188, v56
	v_mul_f32_e32 v57, v189, v57
	v_mul_f32_e32 v58, v190, v58
	v_mul_f32_e32 v59, v191, v59
	v_mul_f32_e32 v52, v52, v48
	v_mul_f32_e32 v53, v53, v49
	v_mul_f32_e32 v54, v54, v50
	v_mul_f32_e32 v55, v55, v51
	v_mul_f32_e32 v56, v52, v56
	v_mul_f32_e32 v57, v53, v57
	v_mul_f32_e32 v58, v54, v58
	v_mul_f32_e32 v59, v55, v59
	v_cvt_pk_bf16_f32 v60, v56, v57
	v_cvt_pk_bf16_f32 v61, v58, v59
	global_store_dwordx2 v234, v[60:61], s[24:25]
	v_lshlrev_b32_e32 v48, 16, v220
	v_and_b32_e32 v49, 0xffff0000, v220
	v_lshlrev_b32_e32 v50, 16, v221
	v_and_b32_e32 v51, 0xffff0000, v221
	v_mul_f32_e32 v52, 0xbfb8aa3b, v48
	v_mul_f32_e32 v53, 0xbfb8aa3b, v49
	v_mul_f32_e32 v54, 0xbfb8aa3b, v50
	v_mul_f32_e32 v55, 0xbfb8aa3b, v51
	v_exp_f32_e32 v52, v52
	v_exp_f32_e32 v53, v53
	v_exp_f32_e32 v54, v54
	v_exp_f32_e32 v55, v55
	v_mul_f32_e32 v56, v20, v46
	v_mul_f32_e32 v57, v21, v46
	v_mul_f32_e32 v58, v22, v46
	v_mul_f32_e32 v59, v23, v46
	v_add_f32_e32 v52, 1.0, v52
	v_add_f32_e32 v53, 1.0, v53
	v_add_f32_e32 v54, 1.0, v54
	v_add_f32_e32 v55, 1.0, v55
	v_rcp_f32_e32 v52, v52
	v_rcp_f32_e32 v53, v53
	v_rcp_f32_e32 v54, v54
	v_rcp_f32_e32 v55, v55
	v_mul_f32_e32 v56, v192, v56
	v_mul_f32_e32 v57, v193, v57
	v_mul_f32_e32 v58, v194, v58
	v_mul_f32_e32 v59, v195, v59
	v_mul_f32_e32 v52, v52, v48
	v_mul_f32_e32 v53, v53, v49
	v_mul_f32_e32 v54, v54, v50
	v_mul_f32_e32 v55, v55, v51
	v_mul_f32_e32 v56, v52, v56
	v_mul_f32_e32 v57, v53, v57
	v_mul_f32_e32 v58, v54, v58
	v_mul_f32_e32 v59, v55, v59
	v_cvt_pk_bf16_f32 v60, v56, v57
	v_cvt_pk_bf16_f32 v61, v58, v59
	s_add_u32 s24, s24, s99
	s_addc_u32 s25, s25, 0
	global_store_dwordx2 v232, v[60:61], s[24:25]
	v_lshlrev_b32_e32 v48, 16, v222
	v_and_b32_e32 v49, 0xffff0000, v222
	v_lshlrev_b32_e32 v50, 16, v223
	v_and_b32_e32 v51, 0xffff0000, v223
	v_mul_f32_e32 v52, 0xbfb8aa3b, v48
	v_mul_f32_e32 v53, 0xbfb8aa3b, v49
	v_mul_f32_e32 v54, 0xbfb8aa3b, v50
	v_mul_f32_e32 v55, 0xbfb8aa3b, v51
	v_exp_f32_e32 v52, v52
	v_exp_f32_e32 v53, v53
	v_exp_f32_e32 v54, v54
	v_exp_f32_e32 v55, v55
	v_mul_f32_e32 v56, v16, v46
	v_mul_f32_e32 v57, v17, v46
	v_mul_f32_e32 v58, v18, v46
	v_mul_f32_e32 v59, v19, v46
	v_add_f32_e32 v52, 1.0, v52
	v_add_f32_e32 v53, 1.0, v53
	v_add_f32_e32 v54, 1.0, v54
	v_add_f32_e32 v55, 1.0, v55
	v_rcp_f32_e32 v52, v52
	v_rcp_f32_e32 v53, v53
	v_rcp_f32_e32 v54, v54
	v_rcp_f32_e32 v55, v55
	v_mul_f32_e32 v56, v196, v56
	v_mul_f32_e32 v57, v197, v57
	v_mul_f32_e32 v58, v198, v58
	v_mul_f32_e32 v59, v199, v59
	v_mul_f32_e32 v52, v52, v48
	v_mul_f32_e32 v53, v53, v49
	v_mul_f32_e32 v54, v54, v50
	v_mul_f32_e32 v55, v55, v51
	v_mul_f32_e32 v56, v52, v56
	v_mul_f32_e32 v57, v53, v57
	v_mul_f32_e32 v58, v54, v58
	v_mul_f32_e32 v59, v55, v59
	v_cvt_pk_bf16_f32 v60, v56, v57
	v_cvt_pk_bf16_f32 v61, v58, v59
	global_store_dwordx2 v234, v[60:61], s[24:25]
	v_lshlrev_b32_e32 v48, 16, v224
	v_and_b32_e32 v49, 0xffff0000, v224
	v_lshlrev_b32_e32 v50, 16, v225
	v_and_b32_e32 v51, 0xffff0000, v225
	v_mul_f32_e32 v52, 0xbfb8aa3b, v48
	v_mul_f32_e32 v53, 0xbfb8aa3b, v49
	v_mul_f32_e32 v54, 0xbfb8aa3b, v50
	v_mul_f32_e32 v55, 0xbfb8aa3b, v51
	v_exp_f32_e32 v52, v52
	v_exp_f32_e32 v53, v53
	v_exp_f32_e32 v54, v54
	v_exp_f32_e32 v55, v55
	v_mul_f32_e32 v56, v12, v46
	v_mul_f32_e32 v57, v13, v46
	v_mul_f32_e32 v58, v14, v46
	v_mul_f32_e32 v59, v15, v46
	v_add_f32_e32 v52, 1.0, v52
	v_add_f32_e32 v53, 1.0, v53
	v_add_f32_e32 v54, 1.0, v54
	v_add_f32_e32 v55, 1.0, v55
	v_rcp_f32_e32 v52, v52
	v_rcp_f32_e32 v53, v53
	v_rcp_f32_e32 v54, v54
	v_rcp_f32_e32 v55, v55
	v_mul_f32_e32 v56, v200, v56
	v_mul_f32_e32 v57, v201, v57
	v_mul_f32_e32 v58, v202, v58
	v_mul_f32_e32 v59, v203, v59
	v_mul_f32_e32 v52, v52, v48
	v_mul_f32_e32 v53, v53, v49
	v_mul_f32_e32 v54, v54, v50
	v_mul_f32_e32 v55, v55, v51
	v_mul_f32_e32 v56, v52, v56
	v_mul_f32_e32 v57, v53, v57
	v_mul_f32_e32 v58, v54, v58
	v_mul_f32_e32 v59, v55, v59
	v_cvt_pk_bf16_f32 v60, v56, v57
	v_cvt_pk_bf16_f32 v61, v58, v59
	s_add_u32 s24, s24, s99
	s_addc_u32 s25, s25, 0
	global_store_dwordx2 v232, v[60:61], s[24:25]
	v_lshlrev_b32_e32 v48, 16, v226
	v_and_b32_e32 v49, 0xffff0000, v226
	v_lshlrev_b32_e32 v50, 16, v227
	v_and_b32_e32 v51, 0xffff0000, v227
	v_mul_f32_e32 v52, 0xbfb8aa3b, v48
	v_mul_f32_e32 v53, 0xbfb8aa3b, v49
	v_mul_f32_e32 v54, 0xbfb8aa3b, v50
	v_mul_f32_e32 v55, 0xbfb8aa3b, v51
	v_exp_f32_e32 v52, v52
	v_exp_f32_e32 v53, v53
	v_exp_f32_e32 v54, v54
	v_exp_f32_e32 v55, v55
	v_mul_f32_e32 v56, v8, v46
	v_mul_f32_e32 v57, v9, v46
	v_mul_f32_e32 v58, v10, v46
	v_mul_f32_e32 v59, v11, v46
	v_add_f32_e32 v52, 1.0, v52
	v_add_f32_e32 v53, 1.0, v53
	v_add_f32_e32 v54, 1.0, v54
	v_add_f32_e32 v55, 1.0, v55
	v_rcp_f32_e32 v52, v52
	v_rcp_f32_e32 v53, v53
	v_rcp_f32_e32 v54, v54
	v_rcp_f32_e32 v55, v55
	v_mul_f32_e32 v56, v204, v56
	v_mul_f32_e32 v57, v205, v57
	v_mul_f32_e32 v58, v206, v58
	v_mul_f32_e32 v59, v207, v59
	v_mul_f32_e32 v52, v52, v48
	v_mul_f32_e32 v53, v53, v49
	v_mul_f32_e32 v54, v54, v50
	v_mul_f32_e32 v55, v55, v51
	v_mul_f32_e32 v56, v52, v56
	v_mul_f32_e32 v57, v53, v57
	v_mul_f32_e32 v58, v54, v58
	v_mul_f32_e32 v59, v55, v59
	v_cvt_pk_bf16_f32 v60, v56, v57
	v_cvt_pk_bf16_f32 v61, v58, v59
	global_store_dwordx2 v234, v[60:61], s[24:25]
	v_lshlrev_b32_e32 v48, 16, v228
	v_and_b32_e32 v49, 0xffff0000, v228
	v_lshlrev_b32_e32 v50, 16, v229
	v_and_b32_e32 v51, 0xffff0000, v229
	v_mul_f32_e32 v52, 0xbfb8aa3b, v48
	v_mul_f32_e32 v53, 0xbfb8aa3b, v49
	v_mul_f32_e32 v54, 0xbfb8aa3b, v50
	v_mul_f32_e32 v55, 0xbfb8aa3b, v51
	v_exp_f32_e32 v52, v52
	v_exp_f32_e32 v53, v53
	v_exp_f32_e32 v54, v54
	v_exp_f32_e32 v55, v55
	v_mul_f32_e32 v56, v4, v46
	v_mul_f32_e32 v57, v5, v46
	v_mul_f32_e32 v58, v6, v46
	v_mul_f32_e32 v59, v7, v46
	v_add_f32_e32 v52, 1.0, v52
	v_add_f32_e32 v53, 1.0, v53
	v_add_f32_e32 v54, 1.0, v54
	v_add_f32_e32 v55, 1.0, v55
	v_rcp_f32_e32 v52, v52
	v_rcp_f32_e32 v53, v53
	v_rcp_f32_e32 v54, v54
	v_rcp_f32_e32 v55, v55
	v_mul_f32_e32 v56, v208, v56
	v_mul_f32_e32 v57, v209, v57
	v_mul_f32_e32 v58, v210, v58
	v_mul_f32_e32 v59, v211, v59
	v_mul_f32_e32 v52, v52, v48
	v_mul_f32_e32 v53, v53, v49
	v_mul_f32_e32 v54, v54, v50
	v_mul_f32_e32 v55, v55, v51
	v_mul_f32_e32 v56, v52, v56
	v_mul_f32_e32 v57, v53, v57
	v_mul_f32_e32 v58, v54, v58
	v_mul_f32_e32 v59, v55, v59
	v_cvt_pk_bf16_f32 v60, v56, v57
	v_cvt_pk_bf16_f32 v61, v58, v59
	s_add_u32 s24, s24, s99
	s_addc_u32 s25, s25, 0
	global_store_dwordx2 v232, v[60:61], s[24:25]
	v_lshlrev_b32_e32 v48, 16, v230
	v_and_b32_e32 v49, 0xffff0000, v230
	v_lshlrev_b32_e32 v50, 16, v231
	v_and_b32_e32 v51, 0xffff0000, v231
	v_mul_f32_e32 v52, 0xbfb8aa3b, v48
	v_mul_f32_e32 v53, 0xbfb8aa3b, v49
	v_mul_f32_e32 v54, 0xbfb8aa3b, v50
	v_mul_f32_e32 v55, 0xbfb8aa3b, v51
	v_exp_f32_e32 v52, v52
	v_exp_f32_e32 v53, v53
	v_exp_f32_e32 v54, v54
	v_exp_f32_e32 v55, v55
	v_mul_f32_e32 v56, v0, v46
	v_mul_f32_e32 v57, v1, v46
	v_mul_f32_e32 v58, v2, v46
	v_mul_f32_e32 v59, v3, v46
	v_add_f32_e32 v52, 1.0, v52
	v_add_f32_e32 v53, 1.0, v53
	v_add_f32_e32 v54, 1.0, v54
	v_add_f32_e32 v55, 1.0, v55
	v_rcp_f32_e32 v52, v52
	v_rcp_f32_e32 v53, v53
	v_rcp_f32_e32 v54, v54
	v_rcp_f32_e32 v55, v55
	v_mul_f32_e32 v56, v212, v56
	v_mul_f32_e32 v57, v213, v57
	v_mul_f32_e32 v58, v214, v58
	v_mul_f32_e32 v59, v215, v59
	v_mul_f32_e32 v52, v52, v48
	v_mul_f32_e32 v53, v53, v49
	v_mul_f32_e32 v54, v54, v50
	v_mul_f32_e32 v55, v55, v51
	v_mul_f32_e32 v56, v52, v56
	v_mul_f32_e32 v57, v53, v57
	v_mul_f32_e32 v58, v54, v58
	v_mul_f32_e32 v59, v55, v59
	v_cvt_pk_bf16_f32 v60, v56, v57
	v_cvt_pk_bf16_f32 v61, v58, v59
	global_store_dwordx2 v234, v[60:61], s[24:25]
	s_branch .LBB0_1087
